# slc tile loop: K/V tiles staged with direct global->LDS loads (global_load_lds_dwordx4) instead of VGPR load + ds_write_b128
# baseline (speedup 1.0000x reference)
; DI float bf2f(bf16 b) { return __uint_as_float(((unsigned)b) << 16); }
; DI void nsa_unit(const Ctx& c0, int b, int g, int i, LAS unsigned char* lds) {
;     ...
;     { const float* ct = (const float*)(c.ws + O_TAB) + (size_t)t * 32; const float* stb = ct + 4096 * 32;
; #pragma unroll
;       for (int s = 0; s < 2; ++s) {
;           const f32x4 c0 = *(const f32x4*)(ct + 16 * s + 8 * hi), c1 = *(const f32x4*)(ct + 16 * s + 8 * hi + 4);
;           const f32x4 s0 = *(const f32x4*)(stb + 16 * s + 8 * hi), s1 = *(const f32x4*)(stb + 16 * s + 8 * hi + 4);
;           float lo_[8], hi_[8], ol[8], oh[8];
; #pragma unroll
;           for (int j = 0; j < 8; ++j) { lo_[j] = bf2f((bf16)qn[s][j]); hi_[j] = bf2f((bf16)qn[s + 2][j]); }
; #pragma unroll
;           for (int j = 0; j < 8; ++j) { const float cc = j < 4 ? c0[j & 3] : c1[j & 3], ss = j < 4 ? s0[j & 3] : s1[j & 3];
;               ol[j] = lo_[j] * cc - hi_[j] * ss; oh[j] = hi_[j] * cc + lo_[j] * ss; }
;           qr[s] = pack8(ol[0], ol[1], ol[2], ol[3], ol[4], ol[5], ol[6], ol[7]); qr[s + 2] = pack8(oh[0], oh[1], oh[2], oh[3], oh[4], oh[5], oh[6], oh[7]); } }
;     ...
;         const bf16* Kg = (const bf16*)(c.ws + O_KS) + ((size_t)g * T + (size_t)b * SEQ) * 64;
;         const bf16* Vg = (const bf16*)(c.ws + O_VS) + ((size_t)g * T + (size_t)b * SEQ) * 64;
;         ASt st; st.m = NEGB; st.l = 0.f; st.o0 = f32x16{}; st.o1 = f32x16{};
;         unsigned long long rem = um;
;         int n = __builtin_ctzll(rem); rem &= rem - 1ull;
;         TileRegs tr = tile_fetch(Kg, Vg, 64 * n, tid);
.LBB0_565:
	v_lshlrev_b64 v[4:5], 7, v[2:3]
	v_lshl_add_u64 v[4:5], s[0:1], 0, v[4:5]
	v_lshlrev_b32_e32 v2, 2, v124
	v_lshl_add_u64 v[16:17], v[4:5], 0, v[2:3]
	s_mov_b64 s[12:13], 0x2200000
	v_add_co_u32_e32 v4, vcc, 0x2200000, v16
	v_lshl_add_u64 v[24:25], v[16:17], 0, s[12:13]
	s_mov_b64 s[12:13], 0x2280000
	v_addc_co_u32_e32 v5, vcc, 0, v17, vcc
	v_lshl_add_u64 v[14:15], v[16:17], 0, s[12:13]
	v_add_co_u32_e32 v16, vcc, 0x2280000, v16
	global_load_dwordx4 v[4:7], v[4:5], off
	s_nop 0
	global_load_dwordx4 v[8:11], v[24:25], off offset:16
	v_addc_co_u32_e32 v17, vcc, 0, v17, vcc
	global_load_dwordx4 v[16:19], v[16:17], off
	s_nop 0
	global_load_dwordx4 v[20:23], v[14:15], off offset:16
	global_load_dwordx4 v[230:233], v[24:25], off offset:64
	global_load_dwordx4 v[234:237], v[24:25], off offset:80
	global_load_dwordx4 v[238:241], v[14:15], off offset:64
	global_load_dwordx4 v[242:245], v[14:15], off offset:80
	v_and_b32_e32 v29, 0xffff0000, v108
	v_lshlrev_b32_e32 v28, 16, v108
	v_and_b32_e32 v27, 0xffff0000, v112
	v_lshlrev_b32_e32 v26, 16, v112
	v_ffbl_b32_e32 v2, v13
	s_add_u32 s12, s0, s94
	v_add_u32_e32 v2, 32, v2
	s_addc_u32 s13, s1, s95
	s_add_u32 s88, s12, 0x8400000
	s_addc_u32 s89, s13, 0
	s_add_u32 s90, s12, 0x9400000
	s_addc_u32 s91, s13, 0
	s_mov_b32 s3, 0
	s_mov_b64 s[12:13], 0
	v_ffbl_b32_e32 v246, v12
	v_min_u32_e32 v52, v246, v2
	v_readlane_b32 s78, v250, 4
	v_readfirstlane_b32 s100, v52
	s_lshl_b32 s79, s78, 1
	v_xor_b32_e32 v246, s79, v150
	v_lshlrev_b32_e32 v246, 7, v246
	s_lshl_b32 s79, s78, 4
	v_or_b32_e32 v246, s79, v246
	s_and_b32 s79, s78, 3
	s_lshl_b32 s79, s79, 4
	v_lshrrev_b32_e32 v247, 2, v150
	v_add_u32_e32 v247, s79, v247
	v_lshlrev_b32_e32 v247, 7, v247
	s_lshr_b32 s79, s78, 2
	s_lshl_b32 s79, s79, 2
	v_and_b32_e32 v249, 3, v150
	v_add_u32_e32 v249, s79, v249
	v_lshl_or_b32 v247, v249, 4, v247
	s_lshl_b32 s82, s100, 13
	s_add_u32 s80, s88, s82
	s_addc_u32 s81, s89, 0
	s_add_u32 s82, s90, s82
	s_addc_u32 s83, s91, 0
	s_lshl_b32 m0, s78, 10
	s_nop 0
	global_load_lds_dwordx4 v246, s[80:81]
	s_add_i32 m0, m0, 0x4000
	s_nop 0
	global_load_lds_dwordx4 v247, s[82:83]
	s_waitcnt vmcnt(6) lgkmcnt(0)
	v_pk_mul_f32 v[30:31], v[16:17], v[28:29]
	s_nop 0
	v_pk_fma_f32 v[30:31], v[4:5], v[26:27], v[30:31] neg_lo:[0,0,1] neg_hi:[0,0,1]
	v_pk_mul_f32 v[16:17], v[16:17], v[26:27]
	v_and_b32_e32 v27, 0xffff0000, v109
	v_lshlrev_b32_e32 v26, 16, v109
	v_pk_fma_f32 v[4:5], v[4:5], v[28:29], v[16:17]
	v_and_b32_e32 v17, 0xffff0000, v113
	v_lshlrev_b32_e32 v16, 16, v113
	v_pk_mul_f32 v[28:29], v[18:19], v[26:27]
	v_cvt_pk_bf16_f32 v86, v4, v5
	v_pk_fma_f32 v[28:29], v[6:7], v[16:17], v[28:29] neg_lo:[0,0,1] neg_hi:[0,0,1]
	v_pk_mul_f32 v[16:17], v[18:19], v[16:17]
	v_and_b32_e32 v19, 0xffff0000, v110
	v_lshlrev_b32_e32 v18, 16, v110
	v_pk_fma_f32 v[6:7], v[6:7], v[26:27], v[16:17]
	v_and_b32_e32 v17, 0xffff0000, v114
	v_lshlrev_b32_e32 v16, 16, v114
	v_pk_mul_f32 v[26:27], v[20:21], v[18:19]
	v_cvt_pk_bf16_f32 v87, v6, v7
	v_pk_fma_f32 v[26:27], v[8:9], v[16:17], v[26:27] neg_lo:[0,0,1] neg_hi:[0,0,1]
	v_pk_mul_f32 v[16:17], v[20:21], v[16:17]
	v_cvt_pk_bf16_f32 v84, v26, v27
	v_pk_fma_f32 v[8:9], v[8:9], v[18:19], v[16:17]
	v_and_b32_e32 v19, 0xffff0000, v111
	v_lshlrev_b32_e32 v18, 16, v111
	v_and_b32_e32 v17, 0xffff0000, v115
	v_lshlrev_b32_e32 v16, 16, v115
	v_pk_mul_f32 v[20:21], v[22:23], v[18:19]
	v_cvt_pk_bf16_f32 v88, v8, v9
	v_pk_fma_f32 v[20:21], v[10:11], v[16:17], v[20:21] neg_lo:[0,0,1] neg_hi:[0,0,1]
	v_pk_mul_f32 v[16:17], v[22:23], v[16:17]
	v_cvt_pk_bf16_f32 v85, v20, v21
	v_pk_fma_f32 v[10:11], v[10:11], v[18:19], v[16:17]
	v_cvt_pk_bf16_f32 v82, v30, v31
	v_cvt_pk_bf16_f32 v89, v10, v11
	v_and_b32_e32 v25, 0xffff0000, v104
	v_lshlrev_b32_e32 v24, 16, v104
	v_and_b32_e32 v15, 0xffff0000, v100
	v_lshlrev_b32_e32 v14, 16, v100
	v_cvt_pk_bf16_f32 v83, v28, v29
	s_waitcnt vmcnt(2) lgkmcnt(0)
	v_pk_mul_f32 v[26:27], v[238:239], v[24:25]
	s_nop 0
	v_pk_fma_f32 v[26:27], v[230:231], v[14:15], v[26:27] neg_lo:[0, 0, 1] neg_hi:[0, 0, 1]
	v_pk_mul_f32 v[14:15], v[238:239], v[14:15]
	v_and_b32_e32 v17, 0xffff0000, v105
	v_lshlrev_b32_e32 v16, 16, v105
	v_pk_fma_f32 v[8:9], v[230:231], v[24:25], v[14:15]
	v_and_b32_e32 v15, 0xffff0000, v101
	v_lshlrev_b32_e32 v14, 16, v101
	v_pk_mul_f32 v[24:25], v[240:241], v[16:17]
	v_cvt_pk_bf16_f32 v90, v26, v27
	v_pk_fma_f32 v[24:25], v[232:233], v[14:15], v[24:25] neg_lo:[0, 0, 1] neg_hi:[0, 0, 1]
	v_pk_mul_f32 v[14:15], v[240:241], v[14:15]
	v_cvt_pk_bf16_f32 v91, v24, v25
	v_pk_fma_f32 v[10:11], v[232:233], v[16:17], v[14:15]
	v_and_b32_e32 v17, 0xffff0000, v106
	v_lshlrev_b32_e32 v16, 16, v106
	v_and_b32_e32 v15, 0xffff0000, v102
	v_lshlrev_b32_e32 v14, 16, v102
	v_pk_mul_f32 v[18:19], v[242:243], v[16:17]
	v_cvt_pk_bf16_f32 v94, v8, v9
	v_pk_fma_f32 v[18:19], v[234:235], v[14:15], v[18:19] neg_lo:[0, 0, 1] neg_hi:[0, 0, 1]
	v_pk_mul_f32 v[14:15], v[242:243], v[14:15]
	v_cvt_pk_bf16_f32 v92, v18, v19
	v_pk_fma_f32 v[4:5], v[234:235], v[16:17], v[14:15]
	v_and_b32_e32 v17, 0xffff0000, v107
	v_cvt_pk_bf16_f32 v96, v4, v5
	v_lshl_add_u64 v[4:5], v[12:13], 0, -1
	v_lshlrev_b32_e32 v16, 16, v107
	v_and_b32_e32 v50, v4, v12
	v_and_b32_e32 v15, 0xffff0000, v103
	v_lshlrev_b32_e32 v14, 16, v103
	v_pk_mul_f32 v[20:21], v[244:245], v[16:17]
	v_and_b32_e32 v51, v5, v13
	v_pk_fma_f32 v[20:21], v[236:237], v[14:15], v[20:21] neg_lo:[0, 0, 1] neg_hi:[0, 0, 1]
	v_pk_mul_f32 v[14:15], v[244:245], v[14:15]
	v_pk_fma_f32 v[6:7], v[236:237], v[16:17], v[14:15]
	v_cvt_pk_bf16_f32 v97, v6, v7
	v_mov_b32_e32 v16, v3
	v_mov_b32_e32 v17, v3
	v_cvt_pk_bf16_f32 v93, v20, v21
	v_cvt_pk_bf16_f32 v95, v10, v11
	v_mov_b32_e32 v2, v3
	v_mov_b32_e32 v4, v3
	v_mov_b32_e32 v5, v3
	v_mov_b32_e32 v6, v3
	v_mov_b32_e32 v7, v3
	v_mov_b32_e32 v8, v3
	v_mov_b32_e32 v9, v3
	v_mov_b32_e32 v10, v3
	v_mov_b32_e32 v11, v3
	v_mov_b32_e32 v12, v3
	v_mov_b32_e32 v13, v3
	v_mov_b32_e32 v14, v3
	v_mov_b32_e32 v15, v3
	v_mov_b64_e32 v[32:33], v[16:17]
	v_mov_b64_e32 v[48:49], v[16:17]
	v_mov_b32_e32 v107, 0xf149f2ca
	v_mov_b32_e32 v106, 0
	v_mov_b64_e32 v[30:31], v[14:15]
	v_mov_b64_e32 v[28:29], v[12:13]
	v_mov_b64_e32 v[26:27], v[10:11]
	v_mov_b64_e32 v[24:25], v[8:9]
	v_mov_b64_e32 v[22:23], v[6:7]
	v_mov_b64_e32 v[20:21], v[4:5]
	v_mov_b64_e32 v[18:19], v[2:3]
	v_mov_b64_e32 v[46:47], v[14:15]
	v_mov_b64_e32 v[44:45], v[12:13]
	v_mov_b64_e32 v[42:43], v[10:11]
	v_mov_b64_e32 v[40:41], v[8:9]
	v_mov_b64_e32 v[38:39], v[6:7]
	v_mov_b64_e32 v[36:37], v[4:5]
	v_mov_b64_e32 v[34:35], v[2:3]
	v_readfirstlane_b32 s98, v50
	v_readfirstlane_b32 s99, v51
	v_readfirstlane_b32 s100, v52
	v_add3_u32 v248, v208, v209, v197
	v_add_u32_e32 v248, v248, v198
	s_branch .LBB0_568

; DI void nsa_unit(const Ctx& c0, int b, int g, int i, LAS unsigned char* lds) {
;     ...
;         for (;;) {
;             tile_stage(tr, lds, k & 1, tid);
;             __syncthreads();
;             const bool more = rem != 0ull; int nn = 0;
;             if (more) { nn = __builtin_ctzll(rem); rem &= rem - 1ull; tr = tile_fetch(Kg, Vg, 64 * nn, tid); }
.LBB0_568:
	s_and_b32 s14, s3, 0x2000
	s_add_i32 s84, s14, 0
	s_cmp_eq_u64 s[98:99], 0
	s_cselect_b64 s[78:79], -1, 0
	s_cselect_b64 vcc, 0, -1
	s_waitcnt vmcnt(0) lgkmcnt(0)
	s_barrier
	s_and_saveexec_b64 s[14:15], vcc
	s_cbranch_execz .LBB0_570
	s_ff1_i32_b64 s101, s[98:99]
	s_add_u32 s80, s98, -1
	s_addc_u32 s81, s99, -1
	s_and_b64 s[98:99], s[98:99], s[80:81]
	s_lshl_b32 s82, s101, 13
	s_add_u32 s80, s88, s82
	s_addc_u32 s81, s89, 0
	s_add_u32 s82, s90, s82
	s_addc_u32 s83, s91, 0
	s_sub_i32 m0, m0, 0x4000
	s_xor_b32 m0, m0, 0x2000
	s_nop 0
	global_load_lds_dwordx4 v246, s[80:81]
	s_add_i32 m0, m0, 0x4000
	s_nop 0
	global_load_lds_dwordx4 v247, s[82:83]

; DI float bf2f(bf16 b) { return __uint_as_float(((unsigned)b) << 16); }
; DI void nsa_unit(const Ctx& c0, int b, int g, int i, LAS unsigned char* lds) {
;     ...
;     { const float* ct = (const float*)(c.ws + O_TAB) + (size_t)t * 32; const float* stb = ct + 4096 * 32;
; #pragma unroll
;       for (int s = 0; s < 2; ++s) {
;           const f32x4 c0 = *(const f32x4*)(ct + 16 * s + 8 * hi), c1 = *(const f32x4*)(ct + 16 * s + 8 * hi + 4);
;           const f32x4 s0 = *(const f32x4*)(stb + 16 * s + 8 * hi), s1 = *(const f32x4*)(stb + 16 * s + 8 * hi + 4);
;           float lo_[8], hi_[8], ol[8], oh[8];
; #pragma unroll
;           for (int j = 0; j < 8; ++j) { lo_[j] = bf2f((bf16)qn[s][j]); hi_[j] = bf2f((bf16)qn[s + 2][j]); }
; #pragma unroll
;           for (int j = 0; j < 8; ++j) { const float cc = j < 4 ? c0[j & 3] : c1[j & 3], ss = j < 4 ? s0[j & 3] : s1[j & 3];
;               ol[j] = lo_[j] * cc - hi_[j] * ss; oh[j] = hi_[j] * cc + lo_[j] * ss; }
;           qr[s] = pack8(ol[0], ol[1], ol[2], ol[3], ol[4], ol[5], ol[6], ol[7]); qr[s + 2] = pack8(oh[0], oh[1], oh[2], oh[3], oh[4], oh[5], oh[6], oh[7]); } }
;     ...
;         const bf16* Kg = (const bf16*)(c.ws + O_KS) + ((size_t)g * T + (size_t)b * SEQ) * 64;
;         const bf16* Vg = (const bf16*)(c.ws + O_VS) + ((size_t)g * T + (size_t)b * SEQ) * 64;
;         ASt st; st.m = NEGB; st.l = 0.f; st.o0 = f32x16{}; st.o1 = f32x16{};
;         unsigned long long rem = um;
;         int n = __builtin_ctzll(rem); rem &= rem - 1ull;
;         TileRegs tr = tile_fetch(Kg, Vg, 64 * n, tid);
.LBB0_1178:
	v_lshlrev_b64 v[4:5], 7, v[2:3]
	v_lshl_add_u64 v[4:5], s[0:1], 0, v[4:5]
	v_lshlrev_b32_e32 v2, 2, v124
	v_lshl_add_u64 v[16:17], v[4:5], 0, v[2:3]
	s_mov_b64 s[14:15], 0x2200000
	v_add_co_u32_e32 v4, vcc, 0x2200000, v16
	v_lshl_add_u64 v[24:25], v[16:17], 0, s[14:15]
	s_mov_b64 s[14:15], 0x2280000
	v_addc_co_u32_e32 v5, vcc, 0, v17, vcc
	v_lshl_add_u64 v[14:15], v[16:17], 0, s[14:15]
	v_add_co_u32_e32 v16, vcc, 0x2280000, v16
	global_load_dwordx4 v[4:7], v[4:5], off
	s_nop 0
	global_load_dwordx4 v[8:11], v[24:25], off offset:16
	v_addc_co_u32_e32 v17, vcc, 0, v17, vcc
	global_load_dwordx4 v[16:19], v[16:17], off
	s_nop 0
	global_load_dwordx4 v[20:23], v[14:15], off offset:16
	global_load_dwordx4 v[230:233], v[24:25], off offset:64
	global_load_dwordx4 v[234:237], v[24:25], off offset:80
	global_load_dwordx4 v[238:241], v[14:15], off offset:64
	global_load_dwordx4 v[242:245], v[14:15], off offset:80
	v_and_b32_e32 v29, 0xffff0000, v108
	v_lshlrev_b32_e32 v28, 16, v108
	v_and_b32_e32 v27, 0xffff0000, v112
	v_lshlrev_b32_e32 v26, 16, v112
	v_ffbl_b32_e32 v2, v13
	s_add_u32 s14, s0, s2
	v_add_u32_e32 v2, 32, v2
	s_addc_u32 s15, s1, s3
	s_add_u32 s88, s14, 0x8400000
	s_addc_u32 s89, s15, 0
	s_add_u32 s90, s14, 0x9400000
	s_addc_u32 s91, s15, 0
	s_mov_b32 s6, 0
	s_mov_b64 s[14:15], 0
	v_ffbl_b32_e32 v246, v12
	v_min_u32_e32 v52, v246, v2
	v_readlane_b32 s80, v250, 4
	v_readfirstlane_b32 s100, v52
	s_lshl_b32 s81, s80, 1
	v_xor_b32_e32 v246, s81, v150
	v_lshlrev_b32_e32 v246, 7, v246
	s_lshl_b32 s81, s80, 4
	v_or_b32_e32 v246, s81, v246
	s_and_b32 s81, s80, 3
	s_lshl_b32 s81, s81, 4
	v_lshrrev_b32_e32 v247, 2, v150
	v_add_u32_e32 v247, s81, v247
	v_lshlrev_b32_e32 v247, 7, v247
	s_lshr_b32 s81, s80, 2
	s_lshl_b32 s81, s81, 2
	v_and_b32_e32 v249, 3, v150
	v_add_u32_e32 v249, s81, v249
	v_lshl_or_b32 v247, v249, 4, v247
	s_lshl_b32 s86, s100, 13
	s_add_u32 s82, s88, s86
	s_addc_u32 s83, s89, 0
	s_add_u32 s86, s90, s86
	s_addc_u32 s87, s91, 0
	s_lshl_b32 m0, s80, 10
	s_nop 0
	global_load_lds_dwordx4 v246, s[82:83]
	s_add_i32 m0, m0, 0x4000
	s_nop 0
	global_load_lds_dwordx4 v247, s[86:87]
	s_waitcnt vmcnt(6) lgkmcnt(0)
	v_pk_mul_f32 v[30:31], v[16:17], v[28:29]
	s_nop 0
	v_pk_fma_f32 v[30:31], v[4:5], v[26:27], v[30:31] neg_lo:[0,0,1] neg_hi:[0,0,1]
	v_pk_mul_f32 v[16:17], v[16:17], v[26:27]
	v_and_b32_e32 v27, 0xffff0000, v109
	v_lshlrev_b32_e32 v26, 16, v109
	v_pk_fma_f32 v[4:5], v[4:5], v[28:29], v[16:17]
	v_and_b32_e32 v17, 0xffff0000, v113
	v_lshlrev_b32_e32 v16, 16, v113
	v_pk_mul_f32 v[28:29], v[18:19], v[26:27]
	v_cvt_pk_bf16_f32 v86, v4, v5
	v_pk_fma_f32 v[28:29], v[6:7], v[16:17], v[28:29] neg_lo:[0,0,1] neg_hi:[0,0,1]
	v_pk_mul_f32 v[16:17], v[18:19], v[16:17]
	v_and_b32_e32 v19, 0xffff0000, v110
	v_lshlrev_b32_e32 v18, 16, v110
	v_pk_fma_f32 v[6:7], v[6:7], v[26:27], v[16:17]
	v_and_b32_e32 v17, 0xffff0000, v114
	v_lshlrev_b32_e32 v16, 16, v114
	v_pk_mul_f32 v[26:27], v[20:21], v[18:19]
	v_cvt_pk_bf16_f32 v87, v6, v7
	v_pk_fma_f32 v[26:27], v[8:9], v[16:17], v[26:27] neg_lo:[0,0,1] neg_hi:[0,0,1]
	v_pk_mul_f32 v[16:17], v[20:21], v[16:17]
	v_cvt_pk_bf16_f32 v84, v26, v27
	v_pk_fma_f32 v[8:9], v[8:9], v[18:19], v[16:17]
	v_and_b32_e32 v19, 0xffff0000, v111
	v_lshlrev_b32_e32 v18, 16, v111
	v_and_b32_e32 v17, 0xffff0000, v115
	v_lshlrev_b32_e32 v16, 16, v115
	v_pk_mul_f32 v[20:21], v[22:23], v[18:19]
	v_cvt_pk_bf16_f32 v88, v8, v9
	v_pk_fma_f32 v[20:21], v[10:11], v[16:17], v[20:21] neg_lo:[0,0,1] neg_hi:[0,0,1]
	v_pk_mul_f32 v[16:17], v[22:23], v[16:17]
	v_cvt_pk_bf16_f32 v85, v20, v21
	v_pk_fma_f32 v[10:11], v[10:11], v[18:19], v[16:17]
	v_cvt_pk_bf16_f32 v82, v30, v31
	v_cvt_pk_bf16_f32 v89, v10, v11
	v_and_b32_e32 v25, 0xffff0000, v104
	v_lshlrev_b32_e32 v24, 16, v104
	v_and_b32_e32 v15, 0xffff0000, v100
	v_lshlrev_b32_e32 v14, 16, v100
	v_cvt_pk_bf16_f32 v83, v28, v29
	s_waitcnt vmcnt(2) lgkmcnt(0)
	v_pk_mul_f32 v[26:27], v[238:239], v[24:25]
	s_nop 0
	v_pk_fma_f32 v[26:27], v[230:231], v[14:15], v[26:27] neg_lo:[0, 0, 1] neg_hi:[0, 0, 1]
	v_pk_mul_f32 v[14:15], v[238:239], v[14:15]
	v_and_b32_e32 v17, 0xffff0000, v105
	v_lshlrev_b32_e32 v16, 16, v105
	v_pk_fma_f32 v[8:9], v[230:231], v[24:25], v[14:15]
	v_and_b32_e32 v15, 0xffff0000, v101
	v_lshlrev_b32_e32 v14, 16, v101
	v_pk_mul_f32 v[24:25], v[240:241], v[16:17]
	v_cvt_pk_bf16_f32 v90, v26, v27
	v_pk_fma_f32 v[24:25], v[232:233], v[14:15], v[24:25] neg_lo:[0, 0, 1] neg_hi:[0, 0, 1]
	v_pk_mul_f32 v[14:15], v[240:241], v[14:15]
	v_cvt_pk_bf16_f32 v91, v24, v25
	v_pk_fma_f32 v[10:11], v[232:233], v[16:17], v[14:15]
	v_and_b32_e32 v17, 0xffff0000, v106
	v_lshlrev_b32_e32 v16, 16, v106
	v_and_b32_e32 v15, 0xffff0000, v102
	v_lshlrev_b32_e32 v14, 16, v102
	v_pk_mul_f32 v[18:19], v[242:243], v[16:17]
	v_cvt_pk_bf16_f32 v94, v8, v9
	v_pk_fma_f32 v[18:19], v[234:235], v[14:15], v[18:19] neg_lo:[0, 0, 1] neg_hi:[0, 0, 1]
	v_pk_mul_f32 v[14:15], v[242:243], v[14:15]
	v_cvt_pk_bf16_f32 v92, v18, v19
	v_pk_fma_f32 v[4:5], v[234:235], v[16:17], v[14:15]
	v_and_b32_e32 v17, 0xffff0000, v107
	v_cvt_pk_bf16_f32 v96, v4, v5
	v_lshl_add_u64 v[4:5], v[12:13], 0, -1
	v_lshlrev_b32_e32 v16, 16, v107
	v_and_b32_e32 v50, v4, v12
	v_and_b32_e32 v15, 0xffff0000, v103
	v_lshlrev_b32_e32 v14, 16, v103
	v_pk_mul_f32 v[20:21], v[244:245], v[16:17]
	v_and_b32_e32 v51, v5, v13
	v_pk_fma_f32 v[20:21], v[236:237], v[14:15], v[20:21] neg_lo:[0, 0, 1] neg_hi:[0, 0, 1]
	v_pk_mul_f32 v[14:15], v[244:245], v[14:15]
	v_pk_fma_f32 v[6:7], v[236:237], v[16:17], v[14:15]
	v_cvt_pk_bf16_f32 v97, v6, v7
	v_mov_b32_e32 v16, v3
	v_mov_b32_e32 v17, v3
	v_cvt_pk_bf16_f32 v93, v20, v21
	v_cvt_pk_bf16_f32 v95, v10, v11
	v_mov_b32_e32 v2, v3
	v_mov_b32_e32 v4, v3
	v_mov_b32_e32 v5, v3
	v_mov_b32_e32 v6, v3
	v_mov_b32_e32 v7, v3
	v_mov_b32_e32 v8, v3
	v_mov_b32_e32 v9, v3
	v_mov_b32_e32 v10, v3
	v_mov_b32_e32 v11, v3
	v_mov_b32_e32 v12, v3
	v_mov_b32_e32 v13, v3
	v_mov_b32_e32 v14, v3
	v_mov_b32_e32 v15, v3
	v_mov_b64_e32 v[32:33], v[16:17]
	v_mov_b64_e32 v[48:49], v[16:17]
	v_mov_b32_e32 v107, 0xf149f2ca
	v_mov_b32_e32 v106, 0
	v_mov_b64_e32 v[30:31], v[14:15]
	v_mov_b64_e32 v[28:29], v[12:13]
	v_mov_b64_e32 v[26:27], v[10:11]
	v_mov_b64_e32 v[24:25], v[8:9]
	v_mov_b64_e32 v[22:23], v[6:7]
	v_mov_b64_e32 v[20:21], v[4:5]
	v_mov_b64_e32 v[18:19], v[2:3]
	v_mov_b64_e32 v[46:47], v[14:15]
	v_mov_b64_e32 v[44:45], v[12:13]
	v_mov_b64_e32 v[42:43], v[10:11]
	v_mov_b64_e32 v[40:41], v[8:9]
	v_mov_b64_e32 v[38:39], v[6:7]
	v_mov_b64_e32 v[36:37], v[4:5]
	v_mov_b64_e32 v[34:35], v[2:3]
	v_readfirstlane_b32 s98, v50
	v_readfirstlane_b32 s99, v51
	v_readfirstlane_b32 s100, v52
	v_add3_u32 v248, v207, v191, v187
	v_add_u32_e32 v248, v248, v186
	s_branch .LBB0_1181

; DI void nsa_unit(const Ctx& c0, int b, int g, int i, LAS unsigned char* lds) {
;     ...
;         for (;;) {
;             tile_stage(tr, lds, k & 1, tid);
;             __syncthreads();
;             const bool more = rem != 0ull; int nn = 0;
;             if (more) { nn = __builtin_ctzll(rem); rem &= rem - 1ull; tr = tile_fetch(Kg, Vg, 64 * nn, tid); }
.LBB0_1181:
	s_and_b32 s16, s6, 0x2000
	s_add_i32 s28, s16, 0
	s_cmp_eq_u64 s[98:99], 0
	s_cselect_b64 s[80:81], -1, 0
	s_cselect_b64 vcc, 0, -1
	s_waitcnt vmcnt(0) lgkmcnt(0)
	s_barrier
	s_and_saveexec_b64 s[16:17], vcc
	s_cbranch_execz .LBB0_1183
	s_ff1_i32_b64 s101, s[98:99]
	s_add_u32 s82, s98, -1
	s_addc_u32 s83, s99, -1
	s_and_b64 s[98:99], s[98:99], s[82:83]
	s_lshl_b32 s86, s101, 13
	s_add_u32 s82, s88, s86
	s_addc_u32 s83, s89, 0
	s_add_u32 s86, s90, s86
	s_addc_u32 s87, s91, 0
	s_sub_i32 m0, m0, 0x4000
	s_xor_b32 m0, m0, 0x2000
	s_nop 0
	global_load_lds_dwordx4 v246, s[82:83]
	s_add_i32 m0, m0, 0x4000
	s_nop 0
	global_load_lds_dwordx4 v247, s[86:87]
